# FFN up GEMM 4-way split-K tail: partial tiles stored write-through (sc0 sc1) and re-read with coherent loads; no L2 writeback / invalidate in the protocol
# baseline (speedup 1.0000x reference)
; #define PG8_BAR __builtin_amdgcn_s_barrier()
; template <class Epi, class Sched, bool ALIGN_EPI = false, bool SP2 = false>
; __device__ __forceinline__ void gemm_phase(PG8_LAS unsigned char* lds, const Gemm g, const Sched& S, const Epi& E) {
;     ...
;         if constexpr (ALIGN_EPI) { if (wr == 0) PG8_BAR; }
;         if constexpr (!Epi::AFTER_DRAIN) { E(acc, cur, wr, wc, fr, fq); S.done(cur); }
.LBB0_1078:
	s_add_i32 s100, s76, -1
	s_mul_i32 s100, s100, s28
	s_add_i32 s100, s100, s2
	s_cmpk_lt_i32 s100, 0x400
	s_cbranch_scc1 .Lup_ep_normal
	s_sub_i32 s100, s100, 0x400
	s_lshl_b32 s101, s100, 18
	s_add_u32 s38, s18, 0x34e00000
	s_addc_u32 s39, s19, 0
	s_add_u32 s38, s38, s101
	s_addc_u32 s39, s39, 0
	v_lshlrev_b32_e32 v152, 4, v218
	global_store_dwordx4 v152, v[0:3], s[38:39] sc0 sc1
	s_add_u32 s38, s38, 0x2000
	s_addc_u32 s39, s39, 0
	global_store_dwordx4 v152, v[4:7], s[38:39] sc0 sc1
	s_add_u32 s38, s38, 0x2000
	s_addc_u32 s39, s39, 0
	global_store_dwordx4 v152, v[8:11], s[38:39] sc0 sc1
	s_add_u32 s38, s38, 0x2000
	s_addc_u32 s39, s39, 0
	global_store_dwordx4 v152, v[12:15], s[38:39] sc0 sc1
	s_add_u32 s38, s38, 0x2000
	s_addc_u32 s39, s39, 0
	global_store_dwordx4 v152, v[16:19], s[38:39] sc0 sc1
	s_add_u32 s38, s38, 0x2000
	s_addc_u32 s39, s39, 0
	global_store_dwordx4 v152, v[20:23], s[38:39] sc0 sc1
	s_add_u32 s38, s38, 0x2000
	s_addc_u32 s39, s39, 0
	global_store_dwordx4 v152, v[24:27], s[38:39] sc0 sc1
	s_add_u32 s38, s38, 0x2000
	s_addc_u32 s39, s39, 0
	global_store_dwordx4 v152, v[28:31], s[38:39] sc0 sc1
	s_add_u32 s38, s38, 0x2000
	s_addc_u32 s39, s39, 0
	global_store_dwordx4 v152, v[32:35], s[38:39] sc0 sc1
	s_add_u32 s38, s38, 0x2000
	s_addc_u32 s39, s39, 0
	global_store_dwordx4 v152, v[36:39], s[38:39] sc0 sc1
	s_add_u32 s38, s38, 0x2000
	s_addc_u32 s39, s39, 0
	global_store_dwordx4 v152, v[40:43], s[38:39] sc0 sc1
	s_add_u32 s38, s38, 0x2000
	s_addc_u32 s39, s39, 0
	global_store_dwordx4 v152, v[44:47], s[38:39] sc0 sc1
	s_add_u32 s38, s38, 0x2000
	s_addc_u32 s39, s39, 0
	global_store_dwordx4 v152, v[48:51], s[38:39] sc0 sc1
	s_add_u32 s38, s38, 0x2000
	s_addc_u32 s39, s39, 0
	global_store_dwordx4 v152, v[52:55], s[38:39] sc0 sc1
	s_add_u32 s38, s38, 0x2000
	s_addc_u32 s39, s39, 0
	global_store_dwordx4 v152, v[56:59], s[38:39] sc0 sc1
	s_add_u32 s38, s38, 0x2000
	s_addc_u32 s39, s39, 0
	global_store_dwordx4 v152, v[60:63], s[38:39] sc0 sc1
	s_add_u32 s38, s38, 0x2000
	s_addc_u32 s39, s39, 0
	global_store_dwordx4 v152, v[64:67], s[38:39] sc0 sc1
	s_add_u32 s38, s38, 0x2000
	s_addc_u32 s39, s39, 0
	global_store_dwordx4 v152, v[68:71], s[38:39] sc0 sc1
	s_add_u32 s38, s38, 0x2000
	s_addc_u32 s39, s39, 0
	global_store_dwordx4 v152, v[72:75], s[38:39] sc0 sc1
	s_add_u32 s38, s38, 0x2000
	s_addc_u32 s39, s39, 0
	global_store_dwordx4 v152, v[76:79], s[38:39] sc0 sc1
	s_add_u32 s38, s38, 0x2000
	s_addc_u32 s39, s39, 0
	global_store_dwordx4 v152, v[80:83], s[38:39] sc0 sc1
	s_add_u32 s38, s38, 0x2000
	s_addc_u32 s39, s39, 0
	global_store_dwordx4 v152, v[84:87], s[38:39] sc0 sc1
	s_add_u32 s38, s38, 0x2000
	s_addc_u32 s39, s39, 0
	global_store_dwordx4 v152, v[88:91], s[38:39] sc0 sc1
	s_add_u32 s38, s38, 0x2000
	s_addc_u32 s39, s39, 0
	global_store_dwordx4 v152, v[92:95], s[38:39] sc0 sc1
	s_add_u32 s38, s38, 0x2000
	s_addc_u32 s39, s39, 0
	global_store_dwordx4 v152, v[96:99], s[38:39] sc0 sc1
	s_add_u32 s38, s38, 0x2000
	s_addc_u32 s39, s39, 0
	global_store_dwordx4 v152, v[100:103], s[38:39] sc0 sc1
	s_add_u32 s38, s38, 0x2000
	s_addc_u32 s39, s39, 0
	global_store_dwordx4 v152, v[104:107], s[38:39] sc0 sc1
	s_add_u32 s38, s38, 0x2000
	s_addc_u32 s39, s39, 0
	global_store_dwordx4 v152, v[108:111], s[38:39] sc0 sc1
	s_add_u32 s38, s38, 0x2000
	s_addc_u32 s39, s39, 0
	global_store_dwordx4 v152, v[112:115], s[38:39] sc0 sc1
	s_add_u32 s38, s38, 0x2000
	s_addc_u32 s39, s39, 0
	global_store_dwordx4 v152, v[116:119], s[38:39] sc0 sc1
	s_add_u32 s38, s38, 0x2000
	s_addc_u32 s39, s39, 0
	global_store_dwordx4 v152, v[120:123], s[38:39] sc0 sc1
	s_add_u32 s38, s38, 0x2000
	s_addc_u32 s39, s39, 0
	global_store_dwordx4 v152, v[124:127], s[38:39] sc0 sc1
	s_add_u32 s38, s38, 0x2000
	s_addc_u32 s39, s39, 0
	s_waitcnt vmcnt(0)
	s_barrier
	v_cmp_eq_u32_e32 vcc, 0, v218
	s_and_saveexec_b64 s[46:47], vcc
	s_cbranch_execz .Lup_sk_atom
	s_lshr_b32 s101, s100, 2
	s_lshl_b32 s101, s101, 2
	s_add_u32 s48, s18, 0x3600
	s_addc_u32 s49, s19, 0
	v_mov_b32_e32 v153, s101
	v_mov_b32_e32 v154, 1
	global_atomic_add v155, v153, v154, s[48:49] sc0
	s_waitcnt vmcnt(0)
	v_mov_b32_e32 v156, 0x23fe0
	ds_write_b32 v156, v155
	s_waitcnt lgkmcnt(0)
.Lup_sk_atom:
	s_mov_b64 exec, s[46:47]
	s_barrier
	v_mov_b32_e32 v156, 0x23fe0
	ds_read_b32 v155, v156
	s_waitcnt lgkmcnt(0)
	v_readfirstlane_b32 s101, v155
	s_nop 3
	s_and_b32 s101, s101, 3
	s_cmp_eq_u32 s101, 3
	s_cbranch_scc0 .Lup_ep_done
; #define PG8_BAR __builtin_amdgcn_s_barrier()
; template <class Epi, class Sched, bool ALIGN_EPI = false, bool SP2 = false>
; __device__ __forceinline__ void gemm_phase(PG8_LAS unsigned char* lds, const Gemm g, const Sched& S, const Epi& E) {
;     ...
;         if constexpr (ALIGN_EPI) { if (wr == 0) PG8_BAR; }
;         if constexpr (!Epi::AFTER_DRAIN) { E(acc, cur, wr, wc, fr, fq); S.done(cur); }
	s_and_b32 s100, s100, 0xfffffffc
	s_lshl_b32 s101, s100, 18
	s_add_u32 s38, s18, 0x34e00000
	s_addc_u32 s39, s19, 0
	s_add_u32 s38, s38, s101
	s_addc_u32 s39, s39, 0
	global_load_dwordx4 v[0:3], v152, s[38:39] sc0 sc1
	s_add_u32 s38, s38, 0x2000
	s_addc_u32 s39, s39, 0
	global_load_dwordx4 v[4:7], v152, s[38:39] sc0 sc1
	s_add_u32 s38, s38, 0x2000
	s_addc_u32 s39, s39, 0
	global_load_dwordx4 v[8:11], v152, s[38:39] sc0 sc1
	s_add_u32 s38, s38, 0x2000
	s_addc_u32 s39, s39, 0
	global_load_dwordx4 v[12:15], v152, s[38:39] sc0 sc1
	s_add_u32 s38, s38, 0x2000
	s_addc_u32 s39, s39, 0
	global_load_dwordx4 v[16:19], v152, s[38:39] sc0 sc1
	s_add_u32 s38, s38, 0x2000
	s_addc_u32 s39, s39, 0
	global_load_dwordx4 v[20:23], v152, s[38:39] sc0 sc1
	s_add_u32 s38, s38, 0x2000
	s_addc_u32 s39, s39, 0
	global_load_dwordx4 v[24:27], v152, s[38:39] sc0 sc1
	s_add_u32 s38, s38, 0x2000
	s_addc_u32 s39, s39, 0
	global_load_dwordx4 v[28:31], v152, s[38:39] sc0 sc1
	s_add_u32 s38, s38, 0x2000
	s_addc_u32 s39, s39, 0
	global_load_dwordx4 v[32:35], v152, s[38:39] sc0 sc1
	s_add_u32 s38, s38, 0x2000
	s_addc_u32 s39, s39, 0
	global_load_dwordx4 v[36:39], v152, s[38:39] sc0 sc1
	s_add_u32 s38, s38, 0x2000
	s_addc_u32 s39, s39, 0
	global_load_dwordx4 v[40:43], v152, s[38:39] sc0 sc1
	s_add_u32 s38, s38, 0x2000
	s_addc_u32 s39, s39, 0
	global_load_dwordx4 v[44:47], v152, s[38:39] sc0 sc1
	s_add_u32 s38, s38, 0x2000
	s_addc_u32 s39, s39, 0
	global_load_dwordx4 v[48:51], v152, s[38:39] sc0 sc1
	s_add_u32 s38, s38, 0x2000
	s_addc_u32 s39, s39, 0
	global_load_dwordx4 v[52:55], v152, s[38:39] sc0 sc1
	s_add_u32 s38, s38, 0x2000
	s_addc_u32 s39, s39, 0
	global_load_dwordx4 v[56:59], v152, s[38:39] sc0 sc1
	s_add_u32 s38, s38, 0x2000
	s_addc_u32 s39, s39, 0
	global_load_dwordx4 v[60:63], v152, s[38:39] sc0 sc1
	s_add_u32 s38, s38, 0x2000
	s_addc_u32 s39, s39, 0
	global_load_dwordx4 v[64:67], v152, s[38:39] sc0 sc1
	s_add_u32 s38, s38, 0x2000
	s_addc_u32 s39, s39, 0
	global_load_dwordx4 v[68:71], v152, s[38:39] sc0 sc1
	s_add_u32 s38, s38, 0x2000
	s_addc_u32 s39, s39, 0
	global_load_dwordx4 v[72:75], v152, s[38:39] sc0 sc1
	s_add_u32 s38, s38, 0x2000
	s_addc_u32 s39, s39, 0
	global_load_dwordx4 v[76:79], v152, s[38:39] sc0 sc1
	s_add_u32 s38, s38, 0x2000
	s_addc_u32 s39, s39, 0
	global_load_dwordx4 v[80:83], v152, s[38:39] sc0 sc1
	s_add_u32 s38, s38, 0x2000
	s_addc_u32 s39, s39, 0
	global_load_dwordx4 v[84:87], v152, s[38:39] sc0 sc1
	s_add_u32 s38, s38, 0x2000
	s_addc_u32 s39, s39, 0
	global_load_dwordx4 v[88:91], v152, s[38:39] sc0 sc1
	s_add_u32 s38, s38, 0x2000
	s_addc_u32 s39, s39, 0
	global_load_dwordx4 v[92:95], v152, s[38:39] sc0 sc1
	s_add_u32 s38, s38, 0x2000
	s_addc_u32 s39, s39, 0
	global_load_dwordx4 v[96:99], v152, s[38:39] sc0 sc1
	s_add_u32 s38, s38, 0x2000
	s_addc_u32 s39, s39, 0
	global_load_dwordx4 v[100:103], v152, s[38:39] sc0 sc1
	s_add_u32 s38, s38, 0x2000
	s_addc_u32 s39, s39, 0
	global_load_dwordx4 v[104:107], v152, s[38:39] sc0 sc1
	s_add_u32 s38, s38, 0x2000
	s_addc_u32 s39, s39, 0
	global_load_dwordx4 v[108:111], v152, s[38:39] sc0 sc1
	s_add_u32 s38, s38, 0x2000
	s_addc_u32 s39, s39, 0
	global_load_dwordx4 v[112:115], v152, s[38:39] sc0 sc1
	s_add_u32 s38, s38, 0x2000
	s_addc_u32 s39, s39, 0
	global_load_dwordx4 v[116:119], v152, s[38:39] sc0 sc1
	s_add_u32 s38, s38, 0x2000
	s_addc_u32 s39, s39, 0
	global_load_dwordx4 v[120:123], v152, s[38:39] sc0 sc1
	s_add_u32 s38, s38, 0x2000
	s_addc_u32 s39, s39, 0
	global_load_dwordx4 v[124:127], v152, s[38:39] sc0 sc1
	s_add_u32 s38, s38, 0x2000
	s_addc_u32 s39, s39, 0
	global_load_dwordx4 v[160:163], v152, s[38:39] sc0 sc1
	s_add_u32 s38, s38, 0x2000
	s_addc_u32 s39, s39, 0
	global_load_dwordx4 v[164:167], v152, s[38:39] sc0 sc1
	s_add_u32 s38, s38, 0x2000
	s_addc_u32 s39, s39, 0
	global_load_dwordx4 v[168:171], v152, s[38:39] sc0 sc1
	s_add_u32 s38, s38, 0x2000
	s_addc_u32 s39, s39, 0
	global_load_dwordx4 v[172:175], v152, s[38:39] sc0 sc1
	s_add_u32 s38, s38, 0x2000
	s_addc_u32 s39, s39, 0
	global_load_dwordx4 v[176:179], v152, s[38:39] sc0 sc1
	s_add_u32 s38, s38, 0x2000
	s_addc_u32 s39, s39, 0
	global_load_dwordx4 v[180:183], v152, s[38:39] sc0 sc1
	s_add_u32 s38, s38, 0x2000
	s_addc_u32 s39, s39, 0
	global_load_dwordx4 v[184:187], v152, s[38:39] sc0 sc1
	s_add_u32 s38, s38, 0x2000
	s_addc_u32 s39, s39, 0
	global_load_dwordx4 v[188:191], v152, s[38:39] sc0 sc1
	s_add_u32 s38, s38, 0x2000
	s_addc_u32 s39, s39, 0
	global_load_dwordx4 v[198:201], v152, s[38:39] sc0 sc1
	s_add_u32 s38, s38, 0x2000
	s_addc_u32 s39, s39, 0
	global_load_dwordx4 v[202:205], v152, s[38:39] sc0 sc1
	s_add_u32 s38, s38, 0x2000
	s_addc_u32 s39, s39, 0
	global_load_dwordx4 v[206:209], v152, s[38:39] sc0 sc1
	s_add_u32 s38, s38, 0x2000
	s_addc_u32 s39, s39, 0
	s_waitcnt vmcnt(0)
; #define PG8_BAR __builtin_amdgcn_s_barrier()
; template <class Epi, class Sched, bool ALIGN_EPI = false, bool SP2 = false>
; __device__ __forceinline__ void gemm_phase(PG8_LAS unsigned char* lds, const Gemm g, const Sched& S, const Epi& E) {
;     ...
;         if constexpr (ALIGN_EPI) { if (wr == 0) PG8_BAR; }
;         if constexpr (!Epi::AFTER_DRAIN) { E(acc, cur, wr, wc, fr, fq); S.done(cur); }
	v_add_f32_e32 v0, v0, v160
	v_add_f32_e32 v1, v1, v161
	v_add_f32_e32 v2, v2, v162
	v_add_f32_e32 v3, v3, v163
	v_add_f32_e32 v4, v4, v164
	v_add_f32_e32 v5, v5, v165
	v_add_f32_e32 v6, v6, v166
	v_add_f32_e32 v7, v7, v167
	v_add_f32_e32 v8, v8, v168
	v_add_f32_e32 v9, v9, v169
	v_add_f32_e32 v10, v10, v170
	v_add_f32_e32 v11, v11, v171
	v_add_f32_e32 v12, v12, v172
	v_add_f32_e32 v13, v13, v173
	v_add_f32_e32 v14, v14, v174
	v_add_f32_e32 v15, v15, v175
	v_add_f32_e32 v16, v16, v176
	v_add_f32_e32 v17, v17, v177
	v_add_f32_e32 v18, v18, v178
	v_add_f32_e32 v19, v19, v179
	v_add_f32_e32 v20, v20, v180
	v_add_f32_e32 v21, v21, v181
	v_add_f32_e32 v22, v22, v182
	v_add_f32_e32 v23, v23, v183
	v_add_f32_e32 v24, v24, v184
	v_add_f32_e32 v25, v25, v185
	v_add_f32_e32 v26, v26, v186
	v_add_f32_e32 v27, v27, v187
	v_add_f32_e32 v28, v28, v188
	v_add_f32_e32 v29, v29, v189
	v_add_f32_e32 v30, v30, v190
	v_add_f32_e32 v31, v31, v191
	v_add_f32_e32 v32, v32, v198
	v_add_f32_e32 v33, v33, v199
	v_add_f32_e32 v34, v34, v200
	v_add_f32_e32 v35, v35, v201
	v_add_f32_e32 v36, v36, v202
	v_add_f32_e32 v37, v37, v203
	v_add_f32_e32 v38, v38, v204
	v_add_f32_e32 v39, v39, v205
	v_add_f32_e32 v40, v40, v206
	v_add_f32_e32 v41, v41, v207
	v_add_f32_e32 v42, v42, v208
	v_add_f32_e32 v43, v43, v209
	global_load_dwordx4 v[160:163], v152, s[38:39] sc0 sc1
	s_add_u32 s38, s38, 0x2000
	s_addc_u32 s39, s39, 0
	global_load_dwordx4 v[164:167], v152, s[38:39] sc0 sc1
	s_add_u32 s38, s38, 0x2000
	s_addc_u32 s39, s39, 0
	global_load_dwordx4 v[168:171], v152, s[38:39] sc0 sc1
	s_add_u32 s38, s38, 0x2000
	s_addc_u32 s39, s39, 0
	global_load_dwordx4 v[172:175], v152, s[38:39] sc0 sc1
	s_add_u32 s38, s38, 0x2000
	s_addc_u32 s39, s39, 0
	global_load_dwordx4 v[176:179], v152, s[38:39] sc0 sc1
	s_add_u32 s38, s38, 0x2000
	s_addc_u32 s39, s39, 0
	global_load_dwordx4 v[180:183], v152, s[38:39] sc0 sc1
	s_add_u32 s38, s38, 0x2000
	s_addc_u32 s39, s39, 0
	global_load_dwordx4 v[184:187], v152, s[38:39] sc0 sc1
	s_add_u32 s38, s38, 0x2000
	s_addc_u32 s39, s39, 0
	global_load_dwordx4 v[188:191], v152, s[38:39] sc0 sc1
	s_add_u32 s38, s38, 0x2000
	s_addc_u32 s39, s39, 0
	global_load_dwordx4 v[198:201], v152, s[38:39] sc0 sc1
	s_add_u32 s38, s38, 0x2000
	s_addc_u32 s39, s39, 0
	global_load_dwordx4 v[202:205], v152, s[38:39] sc0 sc1
	s_add_u32 s38, s38, 0x2000
	s_addc_u32 s39, s39, 0
	global_load_dwordx4 v[206:209], v152, s[38:39] sc0 sc1
	s_add_u32 s38, s38, 0x2000
	s_addc_u32 s39, s39, 0
	s_waitcnt vmcnt(0)
	v_add_f32_e32 v44, v44, v160
	v_add_f32_e32 v45, v45, v161
	v_add_f32_e32 v46, v46, v162
	v_add_f32_e32 v47, v47, v163
	v_add_f32_e32 v48, v48, v164
	v_add_f32_e32 v49, v49, v165
	v_add_f32_e32 v50, v50, v166
	v_add_f32_e32 v51, v51, v167
	v_add_f32_e32 v52, v52, v168
	v_add_f32_e32 v53, v53, v169
	v_add_f32_e32 v54, v54, v170
	v_add_f32_e32 v55, v55, v171
	v_add_f32_e32 v56, v56, v172
	v_add_f32_e32 v57, v57, v173
	v_add_f32_e32 v58, v58, v174
	v_add_f32_e32 v59, v59, v175
	v_add_f32_e32 v60, v60, v176
	v_add_f32_e32 v61, v61, v177
	v_add_f32_e32 v62, v62, v178
	v_add_f32_e32 v63, v63, v179
	v_add_f32_e32 v64, v64, v180
	v_add_f32_e32 v65, v65, v181
	v_add_f32_e32 v66, v66, v182
	v_add_f32_e32 v67, v67, v183
	v_add_f32_e32 v68, v68, v184
	v_add_f32_e32 v69, v69, v185
	v_add_f32_e32 v70, v70, v186
	v_add_f32_e32 v71, v71, v187
	v_add_f32_e32 v72, v72, v188
	v_add_f32_e32 v73, v73, v189
	v_add_f32_e32 v74, v74, v190
	v_add_f32_e32 v75, v75, v191
	v_add_f32_e32 v76, v76, v198
	v_add_f32_e32 v77, v77, v199
	v_add_f32_e32 v78, v78, v200
	v_add_f32_e32 v79, v79, v201
	v_add_f32_e32 v80, v80, v202
	v_add_f32_e32 v81, v81, v203
	v_add_f32_e32 v82, v82, v204
	v_add_f32_e32 v83, v83, v205
	v_add_f32_e32 v84, v84, v206
	v_add_f32_e32 v85, v85, v207
	v_add_f32_e32 v86, v86, v208
	v_add_f32_e32 v87, v87, v209
	global_load_dwordx4 v[160:163], v152, s[38:39] sc0 sc1
	s_add_u32 s38, s38, 0x2000
	s_addc_u32 s39, s39, 0
	global_load_dwordx4 v[164:167], v152, s[38:39] sc0 sc1
	s_add_u32 s38, s38, 0x2000
	s_addc_u32 s39, s39, 0
	global_load_dwordx4 v[168:171], v152, s[38:39] sc0 sc1
	s_add_u32 s38, s38, 0x2000
	s_addc_u32 s39, s39, 0
	global_load_dwordx4 v[172:175], v152, s[38:39] sc0 sc1
	s_add_u32 s38, s38, 0x2000
	s_addc_u32 s39, s39, 0
	global_load_dwordx4 v[176:179], v152, s[38:39] sc0 sc1
	s_add_u32 s38, s38, 0x2000
	s_addc_u32 s39, s39, 0
	global_load_dwordx4 v[180:183], v152, s[38:39] sc0 sc1
	s_add_u32 s38, s38, 0x2000
	s_addc_u32 s39, s39, 0
	global_load_dwordx4 v[184:187], v152, s[38:39] sc0 sc1
	s_add_u32 s38, s38, 0x2000
	s_addc_u32 s39, s39, 0
	global_load_dwordx4 v[188:191], v152, s[38:39] sc0 sc1
	s_add_u32 s38, s38, 0x2000
	s_addc_u32 s39, s39, 0
	global_load_dwordx4 v[198:201], v152, s[38:39] sc0 sc1
	s_add_u32 s38, s38, 0x2000
	s_addc_u32 s39, s39, 0
	global_load_dwordx4 v[202:205], v152, s[38:39] sc0 sc1
	s_add_u32 s38, s38, 0x2000
	s_addc_u32 s39, s39, 0
	s_waitcnt vmcnt(0)
; #define PG8_BAR __builtin_amdgcn_s_barrier()
; template <class Epi, class Sched, bool ALIGN_EPI = false, bool SP2 = false>
; __device__ __forceinline__ void gemm_phase(PG8_LAS unsigned char* lds, const Gemm g, const Sched& S, const Epi& E) {
;     ...
;         if constexpr (ALIGN_EPI) { if (wr == 0) PG8_BAR; }
;         if constexpr (!Epi::AFTER_DRAIN) { E(acc, cur, wr, wc, fr, fq); S.done(cur); }
	v_add_f32_e32 v88, v88, v160
	v_add_f32_e32 v89, v89, v161
	v_add_f32_e32 v90, v90, v162
	v_add_f32_e32 v91, v91, v163
	v_add_f32_e32 v92, v92, v164
	v_add_f32_e32 v93, v93, v165
	v_add_f32_e32 v94, v94, v166
	v_add_f32_e32 v95, v95, v167
	v_add_f32_e32 v96, v96, v168
	v_add_f32_e32 v97, v97, v169
	v_add_f32_e32 v98, v98, v170
	v_add_f32_e32 v99, v99, v171
	v_add_f32_e32 v100, v100, v172
	v_add_f32_e32 v101, v101, v173
	v_add_f32_e32 v102, v102, v174
	v_add_f32_e32 v103, v103, v175
	v_add_f32_e32 v104, v104, v176
	v_add_f32_e32 v105, v105, v177
	v_add_f32_e32 v106, v106, v178
	v_add_f32_e32 v107, v107, v179
	v_add_f32_e32 v108, v108, v180
	v_add_f32_e32 v109, v109, v181
	v_add_f32_e32 v110, v110, v182
	v_add_f32_e32 v111, v111, v183
	v_add_f32_e32 v112, v112, v184
	v_add_f32_e32 v113, v113, v185
	v_add_f32_e32 v114, v114, v186
	v_add_f32_e32 v115, v115, v187
	v_add_f32_e32 v116, v116, v188
	v_add_f32_e32 v117, v117, v189
	v_add_f32_e32 v118, v118, v190
	v_add_f32_e32 v119, v119, v191
	v_add_f32_e32 v120, v120, v198
	v_add_f32_e32 v121, v121, v199
	v_add_f32_e32 v122, v122, v200
	v_add_f32_e32 v123, v123, v201
	v_add_f32_e32 v124, v124, v202
	v_add_f32_e32 v125, v125, v203
	v_add_f32_e32 v126, v126, v204
	v_add_f32_e32 v127, v127, v205
	global_load_dwordx4 v[160:163], v152, s[38:39] sc0 sc1
	s_add_u32 s38, s38, 0x2000
	s_addc_u32 s39, s39, 0
	global_load_dwordx4 v[164:167], v152, s[38:39] sc0 sc1
	s_add_u32 s38, s38, 0x2000
	s_addc_u32 s39, s39, 0
	global_load_dwordx4 v[168:171], v152, s[38:39] sc0 sc1
	s_add_u32 s38, s38, 0x2000
	s_addc_u32 s39, s39, 0
	global_load_dwordx4 v[172:175], v152, s[38:39] sc0 sc1
	s_add_u32 s38, s38, 0x2000
	s_addc_u32 s39, s39, 0
	global_load_dwordx4 v[176:179], v152, s[38:39] sc0 sc1
	s_add_u32 s38, s38, 0x2000
	s_addc_u32 s39, s39, 0
	global_load_dwordx4 v[180:183], v152, s[38:39] sc0 sc1
	s_add_u32 s38, s38, 0x2000
	s_addc_u32 s39, s39, 0
	global_load_dwordx4 v[184:187], v152, s[38:39] sc0 sc1
	s_add_u32 s38, s38, 0x2000
	s_addc_u32 s39, s39, 0
	global_load_dwordx4 v[188:191], v152, s[38:39] sc0 sc1
	s_add_u32 s38, s38, 0x2000
	s_addc_u32 s39, s39, 0
	global_load_dwordx4 v[198:201], v152, s[38:39] sc0 sc1
	s_add_u32 s38, s38, 0x2000
	s_addc_u32 s39, s39, 0
	global_load_dwordx4 v[202:205], v152, s[38:39] sc0 sc1
	s_add_u32 s38, s38, 0x2000
	s_addc_u32 s39, s39, 0
	global_load_dwordx4 v[206:209], v152, s[38:39] sc0 sc1
	s_add_u32 s38, s38, 0x2000
	s_addc_u32 s39, s39, 0
	s_waitcnt vmcnt(0)
	v_add_f32_e32 v0, v0, v160
	v_add_f32_e32 v1, v1, v161
	v_add_f32_e32 v2, v2, v162
	v_add_f32_e32 v3, v3, v163
	v_add_f32_e32 v4, v4, v164
	v_add_f32_e32 v5, v5, v165
	v_add_f32_e32 v6, v6, v166
	v_add_f32_e32 v7, v7, v167
	v_add_f32_e32 v8, v8, v168
	v_add_f32_e32 v9, v9, v169
	v_add_f32_e32 v10, v10, v170
	v_add_f32_e32 v11, v11, v171
	v_add_f32_e32 v12, v12, v172
	v_add_f32_e32 v13, v13, v173
	v_add_f32_e32 v14, v14, v174
	v_add_f32_e32 v15, v15, v175
	v_add_f32_e32 v16, v16, v176
	v_add_f32_e32 v17, v17, v177
	v_add_f32_e32 v18, v18, v178
	v_add_f32_e32 v19, v19, v179
	v_add_f32_e32 v20, v20, v180
	v_add_f32_e32 v21, v21, v181
	v_add_f32_e32 v22, v22, v182
	v_add_f32_e32 v23, v23, v183
	v_add_f32_e32 v24, v24, v184
	v_add_f32_e32 v25, v25, v185
	v_add_f32_e32 v26, v26, v186
	v_add_f32_e32 v27, v27, v187
	v_add_f32_e32 v28, v28, v188
	v_add_f32_e32 v29, v29, v189
	v_add_f32_e32 v30, v30, v190
	v_add_f32_e32 v31, v31, v191
	v_add_f32_e32 v32, v32, v198
	v_add_f32_e32 v33, v33, v199
	v_add_f32_e32 v34, v34, v200
	v_add_f32_e32 v35, v35, v201
	v_add_f32_e32 v36, v36, v202
	v_add_f32_e32 v37, v37, v203
	v_add_f32_e32 v38, v38, v204
	v_add_f32_e32 v39, v39, v205
	v_add_f32_e32 v40, v40, v206
	v_add_f32_e32 v41, v41, v207
	v_add_f32_e32 v42, v42, v208
	v_add_f32_e32 v43, v43, v209
	global_load_dwordx4 v[160:163], v152, s[38:39] sc0 sc1
	s_add_u32 s38, s38, 0x2000
	s_addc_u32 s39, s39, 0
	global_load_dwordx4 v[164:167], v152, s[38:39] sc0 sc1
	s_add_u32 s38, s38, 0x2000
	s_addc_u32 s39, s39, 0
	global_load_dwordx4 v[168:171], v152, s[38:39] sc0 sc1
	s_add_u32 s38, s38, 0x2000
	s_addc_u32 s39, s39, 0
	global_load_dwordx4 v[172:175], v152, s[38:39] sc0 sc1
	s_add_u32 s38, s38, 0x2000
	s_addc_u32 s39, s39, 0
	global_load_dwordx4 v[176:179], v152, s[38:39] sc0 sc1
	s_add_u32 s38, s38, 0x2000
	s_addc_u32 s39, s39, 0
	global_load_dwordx4 v[180:183], v152, s[38:39] sc0 sc1
	s_add_u32 s38, s38, 0x2000
	s_addc_u32 s39, s39, 0
	global_load_dwordx4 v[184:187], v152, s[38:39] sc0 sc1
	s_add_u32 s38, s38, 0x2000
	s_addc_u32 s39, s39, 0
	global_load_dwordx4 v[188:191], v152, s[38:39] sc0 sc1
	s_add_u32 s38, s38, 0x2000
	s_addc_u32 s39, s39, 0
	global_load_dwordx4 v[198:201], v152, s[38:39] sc0 sc1
	s_add_u32 s38, s38, 0x2000
	s_addc_u32 s39, s39, 0
	global_load_dwordx4 v[202:205], v152, s[38:39] sc0 sc1
	s_add_u32 s38, s38, 0x2000
	s_addc_u32 s39, s39, 0
	global_load_dwordx4 v[206:209], v152, s[38:39] sc0 sc1
	s_add_u32 s38, s38, 0x2000
	s_addc_u32 s39, s39, 0
	s_waitcnt vmcnt(0)
; #define PG8_BAR __builtin_amdgcn_s_barrier()
; template <class Epi, class Sched, bool ALIGN_EPI = false, bool SP2 = false>
; __device__ __forceinline__ void gemm_phase(PG8_LAS unsigned char* lds, const Gemm g, const Sched& S, const Epi& E) {
;     ...
;         if constexpr (ALIGN_EPI) { if (wr == 0) PG8_BAR; }
;         if constexpr (!Epi::AFTER_DRAIN) { E(acc, cur, wr, wc, fr, fq); S.done(cur); }
	v_add_f32_e32 v44, v44, v160
	v_add_f32_e32 v45, v45, v161
	v_add_f32_e32 v46, v46, v162
	v_add_f32_e32 v47, v47, v163
	v_add_f32_e32 v48, v48, v164
	v_add_f32_e32 v49, v49, v165
	v_add_f32_e32 v50, v50, v166
	v_add_f32_e32 v51, v51, v167
	v_add_f32_e32 v52, v52, v168
	v_add_f32_e32 v53, v53, v169
	v_add_f32_e32 v54, v54, v170
	v_add_f32_e32 v55, v55, v171
	v_add_f32_e32 v56, v56, v172
	v_add_f32_e32 v57, v57, v173
	v_add_f32_e32 v58, v58, v174
	v_add_f32_e32 v59, v59, v175
	v_add_f32_e32 v60, v60, v176
	v_add_f32_e32 v61, v61, v177
	v_add_f32_e32 v62, v62, v178
	v_add_f32_e32 v63, v63, v179
	v_add_f32_e32 v64, v64, v180
	v_add_f32_e32 v65, v65, v181
	v_add_f32_e32 v66, v66, v182
	v_add_f32_e32 v67, v67, v183
	v_add_f32_e32 v68, v68, v184
	v_add_f32_e32 v69, v69, v185
	v_add_f32_e32 v70, v70, v186
	v_add_f32_e32 v71, v71, v187
	v_add_f32_e32 v72, v72, v188
	v_add_f32_e32 v73, v73, v189
	v_add_f32_e32 v74, v74, v190
	v_add_f32_e32 v75, v75, v191
	v_add_f32_e32 v76, v76, v198
	v_add_f32_e32 v77, v77, v199
	v_add_f32_e32 v78, v78, v200
	v_add_f32_e32 v79, v79, v201
	v_add_f32_e32 v80, v80, v202
	v_add_f32_e32 v81, v81, v203
	v_add_f32_e32 v82, v82, v204
	v_add_f32_e32 v83, v83, v205
	v_add_f32_e32 v84, v84, v206
	v_add_f32_e32 v85, v85, v207
	v_add_f32_e32 v86, v86, v208
	v_add_f32_e32 v87, v87, v209
	global_load_dwordx4 v[160:163], v152, s[38:39] sc0 sc1
	s_add_u32 s38, s38, 0x2000
	s_addc_u32 s39, s39, 0
	global_load_dwordx4 v[164:167], v152, s[38:39] sc0 sc1
	s_add_u32 s38, s38, 0x2000
	s_addc_u32 s39, s39, 0
	global_load_dwordx4 v[168:171], v152, s[38:39] sc0 sc1
	s_add_u32 s38, s38, 0x2000
	s_addc_u32 s39, s39, 0
	global_load_dwordx4 v[172:175], v152, s[38:39] sc0 sc1
	s_add_u32 s38, s38, 0x2000
	s_addc_u32 s39, s39, 0
	global_load_dwordx4 v[176:179], v152, s[38:39] sc0 sc1
	s_add_u32 s38, s38, 0x2000
	s_addc_u32 s39, s39, 0
	global_load_dwordx4 v[180:183], v152, s[38:39] sc0 sc1
	s_add_u32 s38, s38, 0x2000
	s_addc_u32 s39, s39, 0
	global_load_dwordx4 v[184:187], v152, s[38:39] sc0 sc1
	s_add_u32 s38, s38, 0x2000
	s_addc_u32 s39, s39, 0
	global_load_dwordx4 v[188:191], v152, s[38:39] sc0 sc1
	s_add_u32 s38, s38, 0x2000
	s_addc_u32 s39, s39, 0
	global_load_dwordx4 v[198:201], v152, s[38:39] sc0 sc1
	s_add_u32 s38, s38, 0x2000
	s_addc_u32 s39, s39, 0
	global_load_dwordx4 v[202:205], v152, s[38:39] sc0 sc1
	s_add_u32 s38, s38, 0x2000
	s_addc_u32 s39, s39, 0
	s_waitcnt vmcnt(0)
	v_add_f32_e32 v88, v88, v160
	v_add_f32_e32 v89, v89, v161
	v_add_f32_e32 v90, v90, v162
	v_add_f32_e32 v91, v91, v163
	v_add_f32_e32 v92, v92, v164
	v_add_f32_e32 v93, v93, v165
	v_add_f32_e32 v94, v94, v166
	v_add_f32_e32 v95, v95, v167
	v_add_f32_e32 v96, v96, v168
	v_add_f32_e32 v97, v97, v169
	v_add_f32_e32 v98, v98, v170
	v_add_f32_e32 v99, v99, v171
	v_add_f32_e32 v100, v100, v172
	v_add_f32_e32 v101, v101, v173
	v_add_f32_e32 v102, v102, v174
	v_add_f32_e32 v103, v103, v175
	v_add_f32_e32 v104, v104, v176
	v_add_f32_e32 v105, v105, v177
	v_add_f32_e32 v106, v106, v178
	v_add_f32_e32 v107, v107, v179
	v_add_f32_e32 v108, v108, v180
	v_add_f32_e32 v109, v109, v181
	v_add_f32_e32 v110, v110, v182
	v_add_f32_e32 v111, v111, v183
	v_add_f32_e32 v112, v112, v184
	v_add_f32_e32 v113, v113, v185
	v_add_f32_e32 v114, v114, v186
	v_add_f32_e32 v115, v115, v187
	v_add_f32_e32 v116, v116, v188
	v_add_f32_e32 v117, v117, v189
	v_add_f32_e32 v118, v118, v190
	v_add_f32_e32 v119, v119, v191
	v_add_f32_e32 v120, v120, v198
	v_add_f32_e32 v121, v121, v199
	v_add_f32_e32 v122, v122, v200
	v_add_f32_e32 v123, v123, v201
	v_add_f32_e32 v124, v124, v202
	v_add_f32_e32 v125, v125, v203
	v_add_f32_e32 v126, v126, v204
	v_add_f32_e32 v127, v127, v205
	global_load_dwordx4 v[160:163], v152, s[38:39] sc0 sc1
	s_add_u32 s38, s38, 0x2000
	s_addc_u32 s39, s39, 0
	global_load_dwordx4 v[164:167], v152, s[38:39] sc0 sc1
	s_add_u32 s38, s38, 0x2000
	s_addc_u32 s39, s39, 0
	global_load_dwordx4 v[168:171], v152, s[38:39] sc0 sc1
	s_add_u32 s38, s38, 0x2000
	s_addc_u32 s39, s39, 0
	global_load_dwordx4 v[172:175], v152, s[38:39] sc0 sc1
	s_add_u32 s38, s38, 0x2000
	s_addc_u32 s39, s39, 0
	global_load_dwordx4 v[176:179], v152, s[38:39] sc0 sc1
	s_add_u32 s38, s38, 0x2000
	s_addc_u32 s39, s39, 0
	global_load_dwordx4 v[180:183], v152, s[38:39] sc0 sc1
	s_add_u32 s38, s38, 0x2000
	s_addc_u32 s39, s39, 0
	global_load_dwordx4 v[184:187], v152, s[38:39] sc0 sc1
	s_add_u32 s38, s38, 0x2000
	s_addc_u32 s39, s39, 0
	global_load_dwordx4 v[188:191], v152, s[38:39] sc0 sc1
	s_add_u32 s38, s38, 0x2000
	s_addc_u32 s39, s39, 0
	global_load_dwordx4 v[198:201], v152, s[38:39] sc0 sc1
	s_add_u32 s38, s38, 0x2000
	s_addc_u32 s39, s39, 0
	global_load_dwordx4 v[202:205], v152, s[38:39] sc0 sc1
	s_add_u32 s38, s38, 0x2000
	s_addc_u32 s39, s39, 0
	global_load_dwordx4 v[206:209], v152, s[38:39] sc0 sc1
	s_add_u32 s38, s38, 0x2000
	s_addc_u32 s39, s39, 0
	s_waitcnt vmcnt(0)
; #define PG8_BAR __builtin_amdgcn_s_barrier()
; template <class Epi, class Sched, bool ALIGN_EPI = false, bool SP2 = false>
; __device__ __forceinline__ void gemm_phase(PG8_LAS unsigned char* lds, const Gemm g, const Sched& S, const Epi& E) {
;     ...
;         if constexpr (ALIGN_EPI) { if (wr == 0) PG8_BAR; }
;         if constexpr (!Epi::AFTER_DRAIN) { E(acc, cur, wr, wc, fr, fq); S.done(cur); }
	v_add_f32_e32 v0, v0, v160
	v_add_f32_e32 v1, v1, v161
	v_add_f32_e32 v2, v2, v162
	v_add_f32_e32 v3, v3, v163
	v_add_f32_e32 v4, v4, v164
	v_add_f32_e32 v5, v5, v165
	v_add_f32_e32 v6, v6, v166
	v_add_f32_e32 v7, v7, v167
	v_add_f32_e32 v8, v8, v168
	v_add_f32_e32 v9, v9, v169
	v_add_f32_e32 v10, v10, v170
	v_add_f32_e32 v11, v11, v171
	v_add_f32_e32 v12, v12, v172
	v_add_f32_e32 v13, v13, v173
	v_add_f32_e32 v14, v14, v174
	v_add_f32_e32 v15, v15, v175
	v_add_f32_e32 v16, v16, v176
	v_add_f32_e32 v17, v17, v177
	v_add_f32_e32 v18, v18, v178
	v_add_f32_e32 v19, v19, v179
	v_add_f32_e32 v20, v20, v180
	v_add_f32_e32 v21, v21, v181
	v_add_f32_e32 v22, v22, v182
	v_add_f32_e32 v23, v23, v183
	v_add_f32_e32 v24, v24, v184
	v_add_f32_e32 v25, v25, v185
	v_add_f32_e32 v26, v26, v186
	v_add_f32_e32 v27, v27, v187
	v_add_f32_e32 v28, v28, v188
	v_add_f32_e32 v29, v29, v189
	v_add_f32_e32 v30, v30, v190
	v_add_f32_e32 v31, v31, v191
	v_add_f32_e32 v32, v32, v198
	v_add_f32_e32 v33, v33, v199
	v_add_f32_e32 v34, v34, v200
	v_add_f32_e32 v35, v35, v201
	v_add_f32_e32 v36, v36, v202
	v_add_f32_e32 v37, v37, v203
	v_add_f32_e32 v38, v38, v204
	v_add_f32_e32 v39, v39, v205
	v_add_f32_e32 v40, v40, v206
	v_add_f32_e32 v41, v41, v207
	v_add_f32_e32 v42, v42, v208
	v_add_f32_e32 v43, v43, v209
	global_load_dwordx4 v[160:163], v152, s[38:39] sc0 sc1
	s_add_u32 s38, s38, 0x2000
	s_addc_u32 s39, s39, 0
	global_load_dwordx4 v[164:167], v152, s[38:39] sc0 sc1
	s_add_u32 s38, s38, 0x2000
	s_addc_u32 s39, s39, 0
	global_load_dwordx4 v[168:171], v152, s[38:39] sc0 sc1
	s_add_u32 s38, s38, 0x2000
	s_addc_u32 s39, s39, 0
	global_load_dwordx4 v[172:175], v152, s[38:39] sc0 sc1
	s_add_u32 s38, s38, 0x2000
	s_addc_u32 s39, s39, 0
	global_load_dwordx4 v[176:179], v152, s[38:39] sc0 sc1
	s_add_u32 s38, s38, 0x2000
	s_addc_u32 s39, s39, 0
	global_load_dwordx4 v[180:183], v152, s[38:39] sc0 sc1
	s_add_u32 s38, s38, 0x2000
	s_addc_u32 s39, s39, 0
	global_load_dwordx4 v[184:187], v152, s[38:39] sc0 sc1
	s_add_u32 s38, s38, 0x2000
	s_addc_u32 s39, s39, 0
	global_load_dwordx4 v[188:191], v152, s[38:39] sc0 sc1
	s_add_u32 s38, s38, 0x2000
	s_addc_u32 s39, s39, 0
	global_load_dwordx4 v[198:201], v152, s[38:39] sc0 sc1
	s_add_u32 s38, s38, 0x2000
	s_addc_u32 s39, s39, 0
	global_load_dwordx4 v[202:205], v152, s[38:39] sc0 sc1
	s_add_u32 s38, s38, 0x2000
	s_addc_u32 s39, s39, 0
	global_load_dwordx4 v[206:209], v152, s[38:39] sc0 sc1
	s_add_u32 s38, s38, 0x2000
	s_addc_u32 s39, s39, 0
	s_waitcnt vmcnt(0)
	v_add_f32_e32 v44, v44, v160
	v_add_f32_e32 v45, v45, v161
	v_add_f32_e32 v46, v46, v162
	v_add_f32_e32 v47, v47, v163
	v_add_f32_e32 v48, v48, v164
	v_add_f32_e32 v49, v49, v165
	v_add_f32_e32 v50, v50, v166
	v_add_f32_e32 v51, v51, v167
	v_add_f32_e32 v52, v52, v168
	v_add_f32_e32 v53, v53, v169
	v_add_f32_e32 v54, v54, v170
	v_add_f32_e32 v55, v55, v171
	v_add_f32_e32 v56, v56, v172
	v_add_f32_e32 v57, v57, v173
	v_add_f32_e32 v58, v58, v174
	v_add_f32_e32 v59, v59, v175
	v_add_f32_e32 v60, v60, v176
	v_add_f32_e32 v61, v61, v177
	v_add_f32_e32 v62, v62, v178
	v_add_f32_e32 v63, v63, v179
	v_add_f32_e32 v64, v64, v180
	v_add_f32_e32 v65, v65, v181
	v_add_f32_e32 v66, v66, v182
	v_add_f32_e32 v67, v67, v183
	v_add_f32_e32 v68, v68, v184
	v_add_f32_e32 v69, v69, v185
	v_add_f32_e32 v70, v70, v186
	v_add_f32_e32 v71, v71, v187
	v_add_f32_e32 v72, v72, v188
	v_add_f32_e32 v73, v73, v189
	v_add_f32_e32 v74, v74, v190
	v_add_f32_e32 v75, v75, v191
	v_add_f32_e32 v76, v76, v198
	v_add_f32_e32 v77, v77, v199
	v_add_f32_e32 v78, v78, v200
	v_add_f32_e32 v79, v79, v201
	v_add_f32_e32 v80, v80, v202
	v_add_f32_e32 v81, v81, v203
	v_add_f32_e32 v82, v82, v204
	v_add_f32_e32 v83, v83, v205
	v_add_f32_e32 v84, v84, v206
	v_add_f32_e32 v85, v85, v207
	v_add_f32_e32 v86, v86, v208
	v_add_f32_e32 v87, v87, v209
	global_load_dwordx4 v[160:163], v152, s[38:39] sc0 sc1
	s_add_u32 s38, s38, 0x2000
	s_addc_u32 s39, s39, 0
	global_load_dwordx4 v[164:167], v152, s[38:39] sc0 sc1
	s_add_u32 s38, s38, 0x2000
	s_addc_u32 s39, s39, 0
	global_load_dwordx4 v[168:171], v152, s[38:39] sc0 sc1
	s_add_u32 s38, s38, 0x2000
	s_addc_u32 s39, s39, 0
	global_load_dwordx4 v[172:175], v152, s[38:39] sc0 sc1
	s_add_u32 s38, s38, 0x2000
	s_addc_u32 s39, s39, 0
	global_load_dwordx4 v[176:179], v152, s[38:39] sc0 sc1
	s_add_u32 s38, s38, 0x2000
	s_addc_u32 s39, s39, 0
	global_load_dwordx4 v[180:183], v152, s[38:39] sc0 sc1
	s_add_u32 s38, s38, 0x2000
	s_addc_u32 s39, s39, 0
	global_load_dwordx4 v[184:187], v152, s[38:39] sc0 sc1
	s_add_u32 s38, s38, 0x2000
	s_addc_u32 s39, s39, 0
	global_load_dwordx4 v[188:191], v152, s[38:39] sc0 sc1
	s_add_u32 s38, s38, 0x2000
	s_addc_u32 s39, s39, 0
	global_load_dwordx4 v[198:201], v152, s[38:39] sc0 sc1
	s_add_u32 s38, s38, 0x2000
	s_addc_u32 s39, s39, 0
	global_load_dwordx4 v[202:205], v152, s[38:39] sc0 sc1
	s_add_u32 s38, s38, 0x2000
	s_addc_u32 s39, s39, 0
	s_waitcnt vmcnt(0)
	v_add_f32_e32 v88, v88, v160
	v_add_f32_e32 v89, v89, v161
	v_add_f32_e32 v90, v90, v162
	v_add_f32_e32 v91, v91, v163
	v_add_f32_e32 v92, v92, v164
	v_add_f32_e32 v93, v93, v165
	v_add_f32_e32 v94, v94, v166
	v_add_f32_e32 v95, v95, v167
	v_add_f32_e32 v96, v96, v168
	v_add_f32_e32 v97, v97, v169
	v_add_f32_e32 v98, v98, v170
	v_add_f32_e32 v99, v99, v171
	v_add_f32_e32 v100, v100, v172
	v_add_f32_e32 v101, v101, v173
	v_add_f32_e32 v102, v102, v174
	v_add_f32_e32 v103, v103, v175
	v_add_f32_e32 v104, v104, v176
	v_add_f32_e32 v105, v105, v177
	v_add_f32_e32 v106, v106, v178
	v_add_f32_e32 v107, v107, v179
	v_add_f32_e32 v108, v108, v180
	v_add_f32_e32 v109, v109, v181
	v_add_f32_e32 v110, v110, v182
	v_add_f32_e32 v111, v111, v183
	v_add_f32_e32 v112, v112, v184
	v_add_f32_e32 v113, v113, v185
	v_add_f32_e32 v114, v114, v186
	v_add_f32_e32 v115, v115, v187
	v_add_f32_e32 v116, v116, v188
	v_add_f32_e32 v117, v117, v189
	v_add_f32_e32 v118, v118, v190
	v_add_f32_e32 v119, v119, v191
	v_add_f32_e32 v120, v120, v198
	v_add_f32_e32 v121, v121, v199
	v_add_f32_e32 v122, v122, v200
	v_add_f32_e32 v123, v123, v201
	v_add_f32_e32 v124, v124, v202
	v_add_f32_e32 v125, v125, v203
	v_add_f32_e32 v126, v126, v204
	v_add_f32_e32 v127, v127, v205
